# baseline (speedup 1.0000x reference)
; __device__ __forceinline__ float u8f(unsigned w, int i) { return (float)((w >> (8 * i)) & 0xffu) * (1.f / 255.f); }
; #define EPI_BEGIN_S int fo_e = fo, to_e = to; asm volatile("" : "+s"(fo_e), "+s"(to_e));
; __device__ void phase4(const Params& p) {
;     ...
;       const u16* Wp = (const u16*)(ws + (seg == 0 ? OFF_WA : OFF_WB));
;       const u16* Xp = seg == 0 ? ya : yb;
;       const int Kp = seg == 0 ? 2048 : 1024;
;       gemm_tile(Wp, Xp, Kp, fo, to, acc, seg == 0);
;       EPI_BEGIN_S
;       const size_t lanef = (size_t)(fo_e + wr * 64 + fq * 4);
;       if (seg == 0) {
;         #pragma unroll
;         for (int bj = 0; bj < 2; ++bj)
;           #pragma unroll
;           for (int n = 0; n < 2; ++n) {
;             const size_t base = (size_t)EPI_T(bj, n) * D + lanef;
;             const unsigned* pa = reinterpret_cast<const unsigned*>(reinterpret_cast<const unsigned char*>(sga) + base);
;             const unsigned* pb = reinterpret_cast<const unsigned*>(reinterpret_cast<const unsigned char*>(sgb) + base);
;             #pragma unroll
;             for (int ai = 0; ai < 2; ++ai)
;               #pragma unroll
;               for (int m = 0; m < 4; ++m) {
;                 const unsigned ga = pa[(ai * 128 + m * 16) / 4];
;                 const unsigned gb = pb[(ai * 128 + m * 16) / 4];
;                 #pragma unroll
;                 for (int j = 0; j < 4; ++j)
;                   acc[ai][bj][m][n][j] *= u8f(ga, j) * __builtin_amdgcn_rcpf(fmaxf(u8f(gb, j), 1e-30f));
;               }
.LBB0_608:
	s_or_b64 exec, exec, s[50:51]
	v_and_b32_e32 v132, 15, v194
	v_lshrrev_b32_e32 v133, 1, v194
	v_and_b32_e32 v133, 0x60, v133
	v_add3_u32 v132, s18, v132, v133
	v_bfe_u32 v134, v194, 4, 2
	v_lshrrev_b32_e32 v135, 2, v194
	v_and_b32_e32 v135, 0xffffffc0, v135
	v_lshl_add_u32 v136, v134, 4, v135
	v_add_u32_e32 v136, s20, v136
	v_lshl_add_u32 v136, v132, 11, v136
	v_add_u32_e32 v137, 0x8000, v136
	v_add_u32_e32 v138, 0x40000, v136
	v_add_u32_e32 v139, 0x48000, v136
	s_cmp_lg_u32 s79, 0
	s_cbranch_scc1 .Lp4e_seg1
	v_and_b32_e32 v242, 0xff, v194
	v_lshrrev_b32_e32 v243, 8, v194
	v_lshlrev_b32_e32 v243, 7, v243
	v_add_u32_e32 v244, s20, v242
	v_lshl_add_u32 v244, v244, 11, v243
	v_add_u32_e32 v244, 0x3100000, v244
	global_load_dword v246, v244, s[30:31]
	v_add_u32_e32 v245, s18, v242
	v_lshl_add_u32 v245, v245, 11, v243
	global_load_dword v247, v245, s[44:45]
	global_load_dwordx4 v[152:155], v136, s[10:11]
	global_load_dwordx4 v[156:159], v136, s[12:13]
	global_load_dwordx4 v[160:163], v136, s[10:11] offset:128
	global_load_dwordx4 v[164:167], v136, s[12:13] offset:128
	global_load_dwordx4 v[168:171], v137, s[10:11]
	global_load_dwordx4 v[172:175], v137, s[12:13]
	global_load_dwordx4 v[176:179], v137, s[10:11] offset:128
	global_load_dwordx4 v[180:183], v137, s[12:13] offset:128
	global_load_dwordx4 v[184:187], v138, s[10:11]
	global_load_dwordx4 v[188:191], v138, s[12:13]
	global_load_dwordx4 v[196:199], v138, s[10:11] offset:128
	global_load_dwordx4 v[200:203], v138, s[12:13] offset:128
	global_load_dwordx4 v[204:207], v139, s[10:11]
	global_load_dwordx4 v[208:211], v139, s[12:13]
	global_load_dwordx4 v[212:215], v139, s[10:11] offset:128
	global_load_dwordx4 v[216:219], v139, s[12:13] offset:128
	s_waitcnt vmcnt(14)
	v_permlane16_swap_b32 v152, v153
	v_permlane16_swap_b32 v154, v155
	v_permlane16_swap_b32 v156, v157
	v_permlane16_swap_b32 v158, v159
	v_permlane32_swap_b32 v152, v154
	v_permlane32_swap_b32 v153, v155
	v_permlane32_swap_b32 v156, v158
	v_permlane32_swap_b32 v157, v159
	v_cvt_f32_ubyte0_e32 v144, v156
	v_cvt_f32_ubyte1_e32 v145, v156
	v_cvt_f32_ubyte2_e32 v146, v156
	v_cvt_f32_ubyte3_e32 v147, v156
	v_cvt_f32_ubyte0_e32 v140, v152
	v_cvt_f32_ubyte1_e32 v141, v152
	v_cvt_f32_ubyte2_e32 v142, v152
	v_cvt_f32_ubyte3_e32 v143, v152
	v_pk_mul_f32 v[144:145], v[144:145], s[16:17] op_sel_hi:[1,0]
	v_pk_mul_f32 v[146:147], v[146:147], s[16:17] op_sel_hi:[1,0]
	v_pk_mul_f32 v[140:141], v[140:141], s[16:17] op_sel_hi:[1,0]
	v_pk_mul_f32 v[142:143], v[142:143], s[16:17] op_sel_hi:[1,0]
	v_max_f32_e32 v144, 0xda24260, v144
	v_max_f32_e32 v145, 0xda24260, v145
	v_max_f32_e32 v146, 0xda24260, v146
	v_max_f32_e32 v147, 0xda24260, v147
	v_rcp_f32_e32 v144, v144
	v_rcp_f32_e32 v145, v145
	v_rcp_f32_e32 v146, v146
	v_rcp_f32_e32 v147, v147
	v_pk_mul_f32 v[140:141], v[140:141], v[144:145]
	v_pk_mul_f32 v[142:143], v[142:143], v[146:147]
	v_pk_mul_f32 v[128:129], v[128:129], v[140:141]
	v_pk_mul_f32 v[130:131], v[130:131], v[142:143]
	v_cvt_f32_ubyte0_e32 v144, v157
	v_cvt_f32_ubyte1_e32 v145, v157
	v_cvt_f32_ubyte2_e32 v146, v157
	v_cvt_f32_ubyte3_e32 v147, v157
	v_cvt_f32_ubyte0_e32 v140, v153
	v_cvt_f32_ubyte1_e32 v141, v153
	v_cvt_f32_ubyte2_e32 v142, v153
	v_cvt_f32_ubyte3_e32 v143, v153
	v_pk_mul_f32 v[144:145], v[144:145], s[16:17] op_sel_hi:[1,0]
	v_pk_mul_f32 v[146:147], v[146:147], s[16:17] op_sel_hi:[1,0]
	v_pk_mul_f32 v[140:141], v[140:141], s[16:17] op_sel_hi:[1,0]
	v_pk_mul_f32 v[142:143], v[142:143], s[16:17] op_sel_hi:[1,0]
	v_max_f32_e32 v144, 0xda24260, v144
	v_max_f32_e32 v145, 0xda24260, v145
	v_max_f32_e32 v146, 0xda24260, v146
	v_max_f32_e32 v147, 0xda24260, v147
	v_rcp_f32_e32 v144, v144
	v_rcp_f32_e32 v145, v145
	v_rcp_f32_e32 v146, v146
	v_rcp_f32_e32 v147, v147
	v_pk_mul_f32 v[140:141], v[140:141], v[144:145]
	v_pk_mul_f32 v[142:143], v[142:143], v[146:147]
	v_pk_mul_f32 v[120:121], v[120:121], v[140:141]
	v_pk_mul_f32 v[122:123], v[122:123], v[142:143]
	v_cvt_f32_ubyte0_e32 v144, v158
	v_cvt_f32_ubyte1_e32 v145, v158
	v_cvt_f32_ubyte2_e32 v146, v158
	v_cvt_f32_ubyte3_e32 v147, v158
	v_cvt_f32_ubyte0_e32 v140, v154
	v_cvt_f32_ubyte1_e32 v141, v154
	v_cvt_f32_ubyte2_e32 v142, v154
	v_cvt_f32_ubyte3_e32 v143, v154
	v_pk_mul_f32 v[144:145], v[144:145], s[16:17] op_sel_hi:[1,0]
	v_pk_mul_f32 v[146:147], v[146:147], s[16:17] op_sel_hi:[1,0]
	v_pk_mul_f32 v[140:141], v[140:141], s[16:17] op_sel_hi:[1,0]
	v_pk_mul_f32 v[142:143], v[142:143], s[16:17] op_sel_hi:[1,0]
	v_max_f32_e32 v144, 0xda24260, v144
	v_max_f32_e32 v145, 0xda24260, v145
	v_max_f32_e32 v146, 0xda24260, v146
	v_max_f32_e32 v147, 0xda24260, v147
	v_rcp_f32_e32 v144, v144
	v_rcp_f32_e32 v145, v145
	v_rcp_f32_e32 v146, v146
	v_rcp_f32_e32 v147, v147
	v_pk_mul_f32 v[140:141], v[140:141], v[144:145]
	v_pk_mul_f32 v[142:143], v[142:143], v[146:147]
	v_pk_mul_f32 v[112:113], v[112:113], v[140:141]
	v_pk_mul_f32 v[114:115], v[114:115], v[142:143]
	v_cvt_f32_ubyte0_e32 v144, v159
	v_cvt_f32_ubyte1_e32 v145, v159
	v_cvt_f32_ubyte2_e32 v146, v159
	v_cvt_f32_ubyte3_e32 v147, v159
	v_cvt_f32_ubyte0_e32 v140, v155
	v_cvt_f32_ubyte1_e32 v141, v155
	v_cvt_f32_ubyte2_e32 v142, v155
	v_cvt_f32_ubyte3_e32 v143, v155
	v_pk_mul_f32 v[144:145], v[144:145], s[16:17] op_sel_hi:[1,0]
	v_pk_mul_f32 v[146:147], v[146:147], s[16:17] op_sel_hi:[1,0]
	v_pk_mul_f32 v[140:141], v[140:141], s[16:17] op_sel_hi:[1,0]
	v_pk_mul_f32 v[142:143], v[142:143], s[16:17] op_sel_hi:[1,0]
	v_max_f32_e32 v144, 0xda24260, v144
	v_max_f32_e32 v145, 0xda24260, v145
	v_max_f32_e32 v146, 0xda24260, v146
	v_max_f32_e32 v147, 0xda24260, v147
	v_rcp_f32_e32 v144, v144
	v_rcp_f32_e32 v145, v145
	v_rcp_f32_e32 v146, v146
	v_rcp_f32_e32 v147, v147
	v_pk_mul_f32 v[140:141], v[140:141], v[144:145]
	v_pk_mul_f32 v[142:143], v[142:143], v[146:147]
	v_pk_mul_f32 v[104:105], v[104:105], v[140:141]
	v_pk_mul_f32 v[106:107], v[106:107], v[142:143]
	s_waitcnt vmcnt(12)
; __device__ __forceinline__ float u8f(unsigned w, int i) { return (float)((w >> (8 * i)) & 0xffu) * (1.f / 255.f); }
; __device__ void phase4(const Params& p) {
;     ...
;             #pragma unroll
;             for (int ai = 0; ai < 2; ++ai)
;               #pragma unroll
;               for (int m = 0; m < 4; ++m) {
;                 const unsigned ga = pa[(ai * 128 + m * 16) / 4];
;                 const unsigned gb = pb[(ai * 128 + m * 16) / 4];
;                 #pragma unroll
;                 for (int j = 0; j < 4; ++j)
;                   acc[ai][bj][m][n][j] *= u8f(ga, j) * __builtin_amdgcn_rcpf(fmaxf(u8f(gb, j), 1e-30f));
;               }
	v_permlane16_swap_b32 v160, v161
	v_permlane16_swap_b32 v162, v163
	v_permlane16_swap_b32 v164, v165
	v_permlane16_swap_b32 v166, v167
	v_permlane32_swap_b32 v160, v162
	v_permlane32_swap_b32 v161, v163
	v_permlane32_swap_b32 v164, v166
	v_permlane32_swap_b32 v165, v167
	v_cvt_f32_ubyte0_e32 v144, v164
	v_cvt_f32_ubyte1_e32 v145, v164
	v_cvt_f32_ubyte2_e32 v146, v164
	v_cvt_f32_ubyte3_e32 v147, v164
	v_cvt_f32_ubyte0_e32 v140, v160
	v_cvt_f32_ubyte1_e32 v141, v160
	v_cvt_f32_ubyte2_e32 v142, v160
	v_cvt_f32_ubyte3_e32 v143, v160
	v_pk_mul_f32 v[144:145], v[144:145], s[16:17] op_sel_hi:[1,0]
	v_pk_mul_f32 v[146:147], v[146:147], s[16:17] op_sel_hi:[1,0]
	v_pk_mul_f32 v[140:141], v[140:141], s[16:17] op_sel_hi:[1,0]
	v_pk_mul_f32 v[142:143], v[142:143], s[16:17] op_sel_hi:[1,0]
	v_max_f32_e32 v144, 0xda24260, v144
	v_max_f32_e32 v145, 0xda24260, v145
	v_max_f32_e32 v146, 0xda24260, v146
	v_max_f32_e32 v147, 0xda24260, v147
	v_rcp_f32_e32 v144, v144
	v_rcp_f32_e32 v145, v145
	v_rcp_f32_e32 v146, v146
	v_rcp_f32_e32 v147, v147
	v_pk_mul_f32 v[140:141], v[140:141], v[144:145]
	v_pk_mul_f32 v[142:143], v[142:143], v[146:147]
	v_pk_mul_f32 v[64:65], v[64:65], v[140:141]
	v_pk_mul_f32 v[66:67], v[66:67], v[142:143]
	v_cvt_f32_ubyte0_e32 v144, v165
	v_cvt_f32_ubyte1_e32 v145, v165
	v_cvt_f32_ubyte2_e32 v146, v165
	v_cvt_f32_ubyte3_e32 v147, v165
	v_cvt_f32_ubyte0_e32 v140, v161
	v_cvt_f32_ubyte1_e32 v141, v161
	v_cvt_f32_ubyte2_e32 v142, v161
	v_cvt_f32_ubyte3_e32 v143, v161
	v_pk_mul_f32 v[144:145], v[144:145], s[16:17] op_sel_hi:[1,0]
	v_pk_mul_f32 v[146:147], v[146:147], s[16:17] op_sel_hi:[1,0]
	v_pk_mul_f32 v[140:141], v[140:141], s[16:17] op_sel_hi:[1,0]
	v_pk_mul_f32 v[142:143], v[142:143], s[16:17] op_sel_hi:[1,0]
	v_max_f32_e32 v144, 0xda24260, v144
	v_max_f32_e32 v145, 0xda24260, v145
	v_max_f32_e32 v146, 0xda24260, v146
	v_max_f32_e32 v147, 0xda24260, v147
	v_rcp_f32_e32 v144, v144
	v_rcp_f32_e32 v145, v145
	v_rcp_f32_e32 v146, v146
	v_rcp_f32_e32 v147, v147
	v_pk_mul_f32 v[140:141], v[140:141], v[144:145]
	v_pk_mul_f32 v[142:143], v[142:143], v[146:147]
	v_pk_mul_f32 v[56:57], v[56:57], v[140:141]
	v_pk_mul_f32 v[58:59], v[58:59], v[142:143]
	v_cvt_f32_ubyte0_e32 v144, v166
	v_cvt_f32_ubyte1_e32 v145, v166
	v_cvt_f32_ubyte2_e32 v146, v166
	v_cvt_f32_ubyte3_e32 v147, v166
	v_cvt_f32_ubyte0_e32 v140, v162
	v_cvt_f32_ubyte1_e32 v141, v162
	v_cvt_f32_ubyte2_e32 v142, v162
	v_cvt_f32_ubyte3_e32 v143, v162
	v_pk_mul_f32 v[144:145], v[144:145], s[16:17] op_sel_hi:[1,0]
	v_pk_mul_f32 v[146:147], v[146:147], s[16:17] op_sel_hi:[1,0]
	v_pk_mul_f32 v[140:141], v[140:141], s[16:17] op_sel_hi:[1,0]
	v_pk_mul_f32 v[142:143], v[142:143], s[16:17] op_sel_hi:[1,0]
	v_max_f32_e32 v144, 0xda24260, v144
	v_max_f32_e32 v145, 0xda24260, v145
	v_max_f32_e32 v146, 0xda24260, v146
	v_max_f32_e32 v147, 0xda24260, v147
	v_rcp_f32_e32 v144, v144
	v_rcp_f32_e32 v145, v145
	v_rcp_f32_e32 v146, v146
	v_rcp_f32_e32 v147, v147
	v_pk_mul_f32 v[140:141], v[140:141], v[144:145]
	v_pk_mul_f32 v[142:143], v[142:143], v[146:147]
	v_pk_mul_f32 v[48:49], v[48:49], v[140:141]
	v_pk_mul_f32 v[50:51], v[50:51], v[142:143]
	v_cvt_f32_ubyte0_e32 v144, v167
	v_cvt_f32_ubyte1_e32 v145, v167
	v_cvt_f32_ubyte2_e32 v146, v167
	v_cvt_f32_ubyte3_e32 v147, v167
	v_cvt_f32_ubyte0_e32 v140, v163
	v_cvt_f32_ubyte1_e32 v141, v163
	v_cvt_f32_ubyte2_e32 v142, v163
	v_cvt_f32_ubyte3_e32 v143, v163
	v_pk_mul_f32 v[144:145], v[144:145], s[16:17] op_sel_hi:[1,0]
	v_pk_mul_f32 v[146:147], v[146:147], s[16:17] op_sel_hi:[1,0]
	v_pk_mul_f32 v[140:141], v[140:141], s[16:17] op_sel_hi:[1,0]
	v_pk_mul_f32 v[142:143], v[142:143], s[16:17] op_sel_hi:[1,0]
	v_max_f32_e32 v144, 0xda24260, v144
	v_max_f32_e32 v145, 0xda24260, v145
	v_max_f32_e32 v146, 0xda24260, v146
	v_max_f32_e32 v147, 0xda24260, v147
	v_rcp_f32_e32 v144, v144
	v_rcp_f32_e32 v145, v145
	v_rcp_f32_e32 v146, v146
	v_rcp_f32_e32 v147, v147
	v_pk_mul_f32 v[140:141], v[140:141], v[144:145]
	v_pk_mul_f32 v[142:143], v[142:143], v[146:147]
	v_pk_mul_f32 v[40:41], v[40:41], v[140:141]
	v_pk_mul_f32 v[42:43], v[42:43], v[142:143]
	s_waitcnt vmcnt(10)
	v_permlane16_swap_b32 v168, v169
	v_permlane16_swap_b32 v170, v171
	v_permlane16_swap_b32 v172, v173
	v_permlane16_swap_b32 v174, v175
	v_permlane32_swap_b32 v168, v170
	v_permlane32_swap_b32 v169, v171
	v_permlane32_swap_b32 v172, v174
	v_permlane32_swap_b32 v173, v175
	v_cvt_f32_ubyte0_e32 v144, v172
	v_cvt_f32_ubyte1_e32 v145, v172
	v_cvt_f32_ubyte2_e32 v146, v172
	v_cvt_f32_ubyte3_e32 v147, v172
	v_cvt_f32_ubyte0_e32 v140, v168
	v_cvt_f32_ubyte1_e32 v141, v168
	v_cvt_f32_ubyte2_e32 v142, v168
	v_cvt_f32_ubyte3_e32 v143, v168
	v_pk_mul_f32 v[144:145], v[144:145], s[16:17] op_sel_hi:[1,0]
	v_pk_mul_f32 v[146:147], v[146:147], s[16:17] op_sel_hi:[1,0]
	v_pk_mul_f32 v[140:141], v[140:141], s[16:17] op_sel_hi:[1,0]
	v_pk_mul_f32 v[142:143], v[142:143], s[16:17] op_sel_hi:[1,0]
	v_max_f32_e32 v144, 0xda24260, v144
	v_max_f32_e32 v145, 0xda24260, v145
	v_max_f32_e32 v146, 0xda24260, v146
	v_max_f32_e32 v147, 0xda24260, v147
	v_rcp_f32_e32 v144, v144
	v_rcp_f32_e32 v145, v145
	v_rcp_f32_e32 v146, v146
	v_rcp_f32_e32 v147, v147
	v_pk_mul_f32 v[140:141], v[140:141], v[144:145]
	v_pk_mul_f32 v[142:143], v[142:143], v[146:147]
	v_pk_mul_f32 v[124:125], v[124:125], v[140:141]
	v_pk_mul_f32 v[126:127], v[126:127], v[142:143]
	v_cvt_f32_ubyte0_e32 v144, v173
	v_cvt_f32_ubyte1_e32 v145, v173
	v_cvt_f32_ubyte2_e32 v146, v173
	v_cvt_f32_ubyte3_e32 v147, v173
	v_cvt_f32_ubyte0_e32 v140, v169
	v_cvt_f32_ubyte1_e32 v141, v169
	v_cvt_f32_ubyte2_e32 v142, v169
	v_cvt_f32_ubyte3_e32 v143, v169
; __device__ __forceinline__ float u8f(unsigned w, int i) { return (float)((w >> (8 * i)) & 0xffu) * (1.f / 255.f); }
; __device__ void phase4(const Params& p) {
;     ...
;             #pragma unroll
;             for (int ai = 0; ai < 2; ++ai)
;               #pragma unroll
;               for (int m = 0; m < 4; ++m) {
;                 const unsigned ga = pa[(ai * 128 + m * 16) / 4];
;                 const unsigned gb = pb[(ai * 128 + m * 16) / 4];
;                 #pragma unroll
;                 for (int j = 0; j < 4; ++j)
;                   acc[ai][bj][m][n][j] *= u8f(ga, j) * __builtin_amdgcn_rcpf(fmaxf(u8f(gb, j), 1e-30f));
;               }
	v_pk_mul_f32 v[144:145], v[144:145], s[16:17] op_sel_hi:[1,0]
	v_pk_mul_f32 v[146:147], v[146:147], s[16:17] op_sel_hi:[1,0]
	v_pk_mul_f32 v[140:141], v[140:141], s[16:17] op_sel_hi:[1,0]
	v_pk_mul_f32 v[142:143], v[142:143], s[16:17] op_sel_hi:[1,0]
	v_max_f32_e32 v144, 0xda24260, v144
	v_max_f32_e32 v145, 0xda24260, v145
	v_max_f32_e32 v146, 0xda24260, v146
	v_max_f32_e32 v147, 0xda24260, v147
	v_rcp_f32_e32 v144, v144
	v_rcp_f32_e32 v145, v145
	v_rcp_f32_e32 v146, v146
	v_rcp_f32_e32 v147, v147
	v_pk_mul_f32 v[140:141], v[140:141], v[144:145]
	v_pk_mul_f32 v[142:143], v[142:143], v[146:147]
	v_pk_mul_f32 v[116:117], v[116:117], v[140:141]
	v_pk_mul_f32 v[118:119], v[118:119], v[142:143]
	v_cvt_f32_ubyte0_e32 v144, v174
	v_cvt_f32_ubyte1_e32 v145, v174
	v_cvt_f32_ubyte2_e32 v146, v174
	v_cvt_f32_ubyte3_e32 v147, v174
	v_cvt_f32_ubyte0_e32 v140, v170
	v_cvt_f32_ubyte1_e32 v141, v170
	v_cvt_f32_ubyte2_e32 v142, v170
	v_cvt_f32_ubyte3_e32 v143, v170
	v_pk_mul_f32 v[144:145], v[144:145], s[16:17] op_sel_hi:[1,0]
	v_pk_mul_f32 v[146:147], v[146:147], s[16:17] op_sel_hi:[1,0]
	v_pk_mul_f32 v[140:141], v[140:141], s[16:17] op_sel_hi:[1,0]
	v_pk_mul_f32 v[142:143], v[142:143], s[16:17] op_sel_hi:[1,0]
	v_max_f32_e32 v144, 0xda24260, v144
	v_max_f32_e32 v145, 0xda24260, v145
	v_max_f32_e32 v146, 0xda24260, v146
	v_max_f32_e32 v147, 0xda24260, v147
	v_rcp_f32_e32 v144, v144
	v_rcp_f32_e32 v145, v145
	v_rcp_f32_e32 v146, v146
	v_rcp_f32_e32 v147, v147
	v_pk_mul_f32 v[140:141], v[140:141], v[144:145]
	v_pk_mul_f32 v[142:143], v[142:143], v[146:147]
	v_pk_mul_f32 v[108:109], v[108:109], v[140:141]
	v_pk_mul_f32 v[110:111], v[110:111], v[142:143]
	v_cvt_f32_ubyte0_e32 v144, v175
	v_cvt_f32_ubyte1_e32 v145, v175
	v_cvt_f32_ubyte2_e32 v146, v175
	v_cvt_f32_ubyte3_e32 v147, v175
	v_cvt_f32_ubyte0_e32 v140, v171
	v_cvt_f32_ubyte1_e32 v141, v171
	v_cvt_f32_ubyte2_e32 v142, v171
	v_cvt_f32_ubyte3_e32 v143, v171
	v_pk_mul_f32 v[144:145], v[144:145], s[16:17] op_sel_hi:[1,0]
	v_pk_mul_f32 v[146:147], v[146:147], s[16:17] op_sel_hi:[1,0]
	v_pk_mul_f32 v[140:141], v[140:141], s[16:17] op_sel_hi:[1,0]
	v_pk_mul_f32 v[142:143], v[142:143], s[16:17] op_sel_hi:[1,0]
	v_max_f32_e32 v144, 0xda24260, v144
	v_max_f32_e32 v145, 0xda24260, v145
	v_max_f32_e32 v146, 0xda24260, v146
	v_max_f32_e32 v147, 0xda24260, v147
	v_rcp_f32_e32 v144, v144
	v_rcp_f32_e32 v145, v145
	v_rcp_f32_e32 v146, v146
	v_rcp_f32_e32 v147, v147
	v_pk_mul_f32 v[140:141], v[140:141], v[144:145]
	v_pk_mul_f32 v[142:143], v[142:143], v[146:147]
	v_pk_mul_f32 v[100:101], v[100:101], v[140:141]
	v_pk_mul_f32 v[102:103], v[102:103], v[142:143]
	s_waitcnt vmcnt(8)
	v_permlane16_swap_b32 v176, v177
	v_permlane16_swap_b32 v178, v179
	v_permlane16_swap_b32 v180, v181
	v_permlane16_swap_b32 v182, v183
	v_permlane32_swap_b32 v176, v178
	v_permlane32_swap_b32 v177, v179
	v_permlane32_swap_b32 v180, v182
	v_permlane32_swap_b32 v181, v183
	v_cvt_f32_ubyte0_e32 v144, v180
	v_cvt_f32_ubyte1_e32 v145, v180
	v_cvt_f32_ubyte2_e32 v146, v180
	v_cvt_f32_ubyte3_e32 v147, v180
	v_cvt_f32_ubyte0_e32 v140, v176
	v_cvt_f32_ubyte1_e32 v141, v176
	v_cvt_f32_ubyte2_e32 v142, v176
	v_cvt_f32_ubyte3_e32 v143, v176
	v_pk_mul_f32 v[144:145], v[144:145], s[16:17] op_sel_hi:[1,0]
	v_pk_mul_f32 v[146:147], v[146:147], s[16:17] op_sel_hi:[1,0]
	v_pk_mul_f32 v[140:141], v[140:141], s[16:17] op_sel_hi:[1,0]
	v_pk_mul_f32 v[142:143], v[142:143], s[16:17] op_sel_hi:[1,0]
	v_max_f32_e32 v144, 0xda24260, v144
	v_max_f32_e32 v145, 0xda24260, v145
	v_max_f32_e32 v146, 0xda24260, v146
	v_max_f32_e32 v147, 0xda24260, v147
	v_rcp_f32_e32 v144, v144
	v_rcp_f32_e32 v145, v145
	v_rcp_f32_e32 v146, v146
	v_rcp_f32_e32 v147, v147
	v_pk_mul_f32 v[140:141], v[140:141], v[144:145]
	v_pk_mul_f32 v[142:143], v[142:143], v[146:147]
	v_pk_mul_f32 v[60:61], v[60:61], v[140:141]
	v_pk_mul_f32 v[62:63], v[62:63], v[142:143]
	v_cvt_f32_ubyte0_e32 v144, v181
	v_cvt_f32_ubyte1_e32 v145, v181
	v_cvt_f32_ubyte2_e32 v146, v181
	v_cvt_f32_ubyte3_e32 v147, v181
	v_cvt_f32_ubyte0_e32 v140, v177
	v_cvt_f32_ubyte1_e32 v141, v177
	v_cvt_f32_ubyte2_e32 v142, v177
	v_cvt_f32_ubyte3_e32 v143, v177
	v_pk_mul_f32 v[144:145], v[144:145], s[16:17] op_sel_hi:[1,0]
	v_pk_mul_f32 v[146:147], v[146:147], s[16:17] op_sel_hi:[1,0]
	v_pk_mul_f32 v[140:141], v[140:141], s[16:17] op_sel_hi:[1,0]
	v_pk_mul_f32 v[142:143], v[142:143], s[16:17] op_sel_hi:[1,0]
	v_max_f32_e32 v144, 0xda24260, v144
	v_max_f32_e32 v145, 0xda24260, v145
	v_max_f32_e32 v146, 0xda24260, v146
	v_max_f32_e32 v147, 0xda24260, v147
	v_rcp_f32_e32 v144, v144
	v_rcp_f32_e32 v145, v145
	v_rcp_f32_e32 v146, v146
	v_rcp_f32_e32 v147, v147
	v_pk_mul_f32 v[140:141], v[140:141], v[144:145]
	v_pk_mul_f32 v[142:143], v[142:143], v[146:147]
	v_pk_mul_f32 v[52:53], v[52:53], v[140:141]
	v_pk_mul_f32 v[54:55], v[54:55], v[142:143]
	v_cvt_f32_ubyte0_e32 v144, v182
	v_cvt_f32_ubyte1_e32 v145, v182
	v_cvt_f32_ubyte2_e32 v146, v182
	v_cvt_f32_ubyte3_e32 v147, v182
	v_cvt_f32_ubyte0_e32 v140, v178
	v_cvt_f32_ubyte1_e32 v141, v178
	v_cvt_f32_ubyte2_e32 v142, v178
	v_cvt_f32_ubyte3_e32 v143, v178
	v_pk_mul_f32 v[144:145], v[144:145], s[16:17] op_sel_hi:[1,0]
	v_pk_mul_f32 v[146:147], v[146:147], s[16:17] op_sel_hi:[1,0]
	v_pk_mul_f32 v[140:141], v[140:141], s[16:17] op_sel_hi:[1,0]
	v_pk_mul_f32 v[142:143], v[142:143], s[16:17] op_sel_hi:[1,0]
	v_max_f32_e32 v144, 0xda24260, v144
	v_max_f32_e32 v145, 0xda24260, v145
	v_max_f32_e32 v146, 0xda24260, v146
	v_max_f32_e32 v147, 0xda24260, v147
	v_rcp_f32_e32 v144, v144
	v_rcp_f32_e32 v145, v145
	v_rcp_f32_e32 v146, v146
	v_rcp_f32_e32 v147, v147
	v_pk_mul_f32 v[140:141], v[140:141], v[144:145]
	v_pk_mul_f32 v[142:143], v[142:143], v[146:147]
	v_pk_mul_f32 v[44:45], v[44:45], v[140:141]
	v_pk_mul_f32 v[46:47], v[46:47], v[142:143]
	v_cvt_f32_ubyte0_e32 v144, v183
	v_cvt_f32_ubyte1_e32 v145, v183
	v_cvt_f32_ubyte2_e32 v146, v183
	v_cvt_f32_ubyte3_e32 v147, v183
	v_cvt_f32_ubyte0_e32 v140, v179
	v_cvt_f32_ubyte1_e32 v141, v179
	v_cvt_f32_ubyte2_e32 v142, v179
	v_cvt_f32_ubyte3_e32 v143, v179
	v_pk_mul_f32 v[144:145], v[144:145], s[16:17] op_sel_hi:[1,0]
	v_pk_mul_f32 v[146:147], v[146:147], s[16:17] op_sel_hi:[1,0]
	v_pk_mul_f32 v[140:141], v[140:141], s[16:17] op_sel_hi:[1,0]
	v_pk_mul_f32 v[142:143], v[142:143], s[16:17] op_sel_hi:[1,0]
	v_max_f32_e32 v144, 0xda24260, v144
	v_max_f32_e32 v145, 0xda24260, v145
	v_max_f32_e32 v146, 0xda24260, v146
	v_max_f32_e32 v147, 0xda24260, v147
	v_rcp_f32_e32 v144, v144
	v_rcp_f32_e32 v145, v145
	v_rcp_f32_e32 v146, v146
	v_rcp_f32_e32 v147, v147
	v_pk_mul_f32 v[140:141], v[140:141], v[144:145]
	v_pk_mul_f32 v[142:143], v[142:143], v[146:147]
	v_pk_mul_f32 v[36:37], v[36:37], v[140:141]
	v_pk_mul_f32 v[38:39], v[38:39], v[142:143]
	s_waitcnt vmcnt(6)
; __device__ __forceinline__ float u8f(unsigned w, int i) { return (float)((w >> (8 * i)) & 0xffu) * (1.f / 255.f); }
; __device__ void phase4(const Params& p) {
;     ...
;       if (seg == 0) {
;         #pragma unroll
;         for (int bj = 0; bj < 2; ++bj)
;           #pragma unroll
;           for (int n = 0; n < 2; ++n) {
;             const size_t base = (size_t)EPI_T(bj, n) * D + lanef;
;             const unsigned* pa = reinterpret_cast<const unsigned*>(reinterpret_cast<const unsigned char*>(sga) + base);
;             const unsigned* pb = reinterpret_cast<const unsigned*>(reinterpret_cast<const unsigned char*>(sgb) + base);
;             #pragma unroll
;             for (int ai = 0; ai < 2; ++ai)
;               #pragma unroll
;               for (int m = 0; m < 4; ++m) {
;                 const unsigned ga = pa[(ai * 128 + m * 16) / 4];
;                 const unsigned gb = pb[(ai * 128 + m * 16) / 4];
;                 #pragma unroll
;                 for (int j = 0; j < 4; ++j)
;                   acc[ai][bj][m][n][j] *= u8f(ga, j) * __builtin_amdgcn_rcpf(fmaxf(u8f(gb, j), 1e-30f));
;               }
;             asm volatile("" ::: "memory");
;           }
	v_permlane16_swap_b32 v184, v185
	v_permlane16_swap_b32 v186, v187
	v_permlane16_swap_b32 v188, v189
	v_permlane16_swap_b32 v190, v191
	v_permlane32_swap_b32 v184, v186
	v_permlane32_swap_b32 v185, v187
	v_permlane32_swap_b32 v188, v190
	v_permlane32_swap_b32 v189, v191
	v_cvt_f32_ubyte0_e32 v144, v188
	v_cvt_f32_ubyte1_e32 v145, v188
	v_cvt_f32_ubyte2_e32 v146, v188
	v_cvt_f32_ubyte3_e32 v147, v188
	v_cvt_f32_ubyte0_e32 v140, v184
	v_cvt_f32_ubyte1_e32 v141, v184
	v_cvt_f32_ubyte2_e32 v142, v184
	v_cvt_f32_ubyte3_e32 v143, v184
	v_pk_mul_f32 v[144:145], v[144:145], s[16:17] op_sel_hi:[1,0]
	v_pk_mul_f32 v[146:147], v[146:147], s[16:17] op_sel_hi:[1,0]
	v_pk_mul_f32 v[140:141], v[140:141], s[16:17] op_sel_hi:[1,0]
	v_pk_mul_f32 v[142:143], v[142:143], s[16:17] op_sel_hi:[1,0]
	v_max_f32_e32 v144, 0xda24260, v144
	v_max_f32_e32 v145, 0xda24260, v145
	v_max_f32_e32 v146, 0xda24260, v146
	v_max_f32_e32 v147, 0xda24260, v147
	v_rcp_f32_e32 v144, v144
	v_rcp_f32_e32 v145, v145
	v_rcp_f32_e32 v146, v146
	v_rcp_f32_e32 v147, v147
	v_pk_mul_f32 v[140:141], v[140:141], v[144:145]
	v_pk_mul_f32 v[142:143], v[142:143], v[146:147]
	v_pk_mul_f32 v[96:97], v[96:97], v[140:141]
	v_pk_mul_f32 v[98:99], v[98:99], v[142:143]
	v_cvt_f32_ubyte0_e32 v144, v189
	v_cvt_f32_ubyte1_e32 v145, v189
	v_cvt_f32_ubyte2_e32 v146, v189
	v_cvt_f32_ubyte3_e32 v147, v189
	v_cvt_f32_ubyte0_e32 v140, v185
	v_cvt_f32_ubyte1_e32 v141, v185
	v_cvt_f32_ubyte2_e32 v142, v185
	v_cvt_f32_ubyte3_e32 v143, v185
	v_pk_mul_f32 v[144:145], v[144:145], s[16:17] op_sel_hi:[1,0]
	v_pk_mul_f32 v[146:147], v[146:147], s[16:17] op_sel_hi:[1,0]
	v_pk_mul_f32 v[140:141], v[140:141], s[16:17] op_sel_hi:[1,0]
	v_pk_mul_f32 v[142:143], v[142:143], s[16:17] op_sel_hi:[1,0]
	v_max_f32_e32 v144, 0xda24260, v144
	v_max_f32_e32 v145, 0xda24260, v145
	v_max_f32_e32 v146, 0xda24260, v146
	v_max_f32_e32 v147, 0xda24260, v147
	v_rcp_f32_e32 v144, v144
	v_rcp_f32_e32 v145, v145
	v_rcp_f32_e32 v146, v146
	v_rcp_f32_e32 v147, v147
	v_pk_mul_f32 v[140:141], v[140:141], v[144:145]
	v_pk_mul_f32 v[142:143], v[142:143], v[146:147]
	v_pk_mul_f32 v[88:89], v[88:89], v[140:141]
	v_pk_mul_f32 v[90:91], v[90:91], v[142:143]
	v_cvt_f32_ubyte0_e32 v144, v190
	v_cvt_f32_ubyte1_e32 v145, v190
	v_cvt_f32_ubyte2_e32 v146, v190
	v_cvt_f32_ubyte3_e32 v147, v190
	v_cvt_f32_ubyte0_e32 v140, v186
	v_cvt_f32_ubyte1_e32 v141, v186
	v_cvt_f32_ubyte2_e32 v142, v186
	v_cvt_f32_ubyte3_e32 v143, v186
	v_pk_mul_f32 v[144:145], v[144:145], s[16:17] op_sel_hi:[1,0]
	v_pk_mul_f32 v[146:147], v[146:147], s[16:17] op_sel_hi:[1,0]
	v_pk_mul_f32 v[140:141], v[140:141], s[16:17] op_sel_hi:[1,0]
	v_pk_mul_f32 v[142:143], v[142:143], s[16:17] op_sel_hi:[1,0]
	v_max_f32_e32 v144, 0xda24260, v144
	v_max_f32_e32 v145, 0xda24260, v145
	v_max_f32_e32 v146, 0xda24260, v146
	v_max_f32_e32 v147, 0xda24260, v147
	v_rcp_f32_e32 v144, v144
	v_rcp_f32_e32 v145, v145
	v_rcp_f32_e32 v146, v146
	v_rcp_f32_e32 v147, v147
	v_pk_mul_f32 v[140:141], v[140:141], v[144:145]
	v_pk_mul_f32 v[142:143], v[142:143], v[146:147]
	v_pk_mul_f32 v[80:81], v[80:81], v[140:141]
	v_pk_mul_f32 v[82:83], v[82:83], v[142:143]
	v_cvt_f32_ubyte0_e32 v144, v191
	v_cvt_f32_ubyte1_e32 v145, v191
	v_cvt_f32_ubyte2_e32 v146, v191
	v_cvt_f32_ubyte3_e32 v147, v191
	v_cvt_f32_ubyte0_e32 v140, v187
	v_cvt_f32_ubyte1_e32 v141, v187
	v_cvt_f32_ubyte2_e32 v142, v187
	v_cvt_f32_ubyte3_e32 v143, v187
	v_pk_mul_f32 v[144:145], v[144:145], s[16:17] op_sel_hi:[1,0]
	v_pk_mul_f32 v[146:147], v[146:147], s[16:17] op_sel_hi:[1,0]
	v_pk_mul_f32 v[140:141], v[140:141], s[16:17] op_sel_hi:[1,0]
	v_pk_mul_f32 v[142:143], v[142:143], s[16:17] op_sel_hi:[1,0]
	v_max_f32_e32 v144, 0xda24260, v144
	v_max_f32_e32 v145, 0xda24260, v145
	v_max_f32_e32 v146, 0xda24260, v146
	v_max_f32_e32 v147, 0xda24260, v147
	v_rcp_f32_e32 v144, v144
	v_rcp_f32_e32 v145, v145
	v_rcp_f32_e32 v146, v146
	v_rcp_f32_e32 v147, v147
	v_pk_mul_f32 v[140:141], v[140:141], v[144:145]
	v_pk_mul_f32 v[142:143], v[142:143], v[146:147]
	v_pk_mul_f32 v[72:73], v[72:73], v[140:141]
	v_pk_mul_f32 v[74:75], v[74:75], v[142:143]
	s_waitcnt vmcnt(4)
	v_permlane16_swap_b32 v196, v197
	v_permlane16_swap_b32 v198, v199
	v_permlane16_swap_b32 v200, v201
	v_permlane16_swap_b32 v202, v203
	v_permlane32_swap_b32 v196, v198
	v_permlane32_swap_b32 v197, v199
	v_permlane32_swap_b32 v200, v202
	v_permlane32_swap_b32 v201, v203
	v_cvt_f32_ubyte0_e32 v144, v200
	v_cvt_f32_ubyte1_e32 v145, v200
	v_cvt_f32_ubyte2_e32 v146, v200
	v_cvt_f32_ubyte3_e32 v147, v200
	v_cvt_f32_ubyte0_e32 v140, v196
	v_cvt_f32_ubyte1_e32 v141, v196
	v_cvt_f32_ubyte2_e32 v142, v196
	v_cvt_f32_ubyte3_e32 v143, v196
	v_pk_mul_f32 v[144:145], v[144:145], s[16:17] op_sel_hi:[1,0]
	v_pk_mul_f32 v[146:147], v[146:147], s[16:17] op_sel_hi:[1,0]
	v_pk_mul_f32 v[140:141], v[140:141], s[16:17] op_sel_hi:[1,0]
	v_pk_mul_f32 v[142:143], v[142:143], s[16:17] op_sel_hi:[1,0]
	v_max_f32_e32 v144, 0xda24260, v144
	v_max_f32_e32 v145, 0xda24260, v145
	v_max_f32_e32 v146, 0xda24260, v146
	v_max_f32_e32 v147, 0xda24260, v147
	v_rcp_f32_e32 v144, v144
	v_rcp_f32_e32 v145, v145
	v_rcp_f32_e32 v146, v146
	v_rcp_f32_e32 v147, v147
	v_pk_mul_f32 v[140:141], v[140:141], v[144:145]
	v_pk_mul_f32 v[142:143], v[142:143], v[146:147]
	v_pk_mul_f32 v[32:33], v[32:33], v[140:141]
	v_pk_mul_f32 v[34:35], v[34:35], v[142:143]
	v_cvt_f32_ubyte0_e32 v144, v201
	v_cvt_f32_ubyte1_e32 v145, v201
	v_cvt_f32_ubyte2_e32 v146, v201
	v_cvt_f32_ubyte3_e32 v147, v201
	v_cvt_f32_ubyte0_e32 v140, v197
	v_cvt_f32_ubyte1_e32 v141, v197
	v_cvt_f32_ubyte2_e32 v142, v197
	v_cvt_f32_ubyte3_e32 v143, v197
	v_pk_mul_f32 v[144:145], v[144:145], s[16:17] op_sel_hi:[1,0]
; __device__ __forceinline__ float u8f(unsigned w, int i) { return (float)((w >> (8 * i)) & 0xffu) * (1.f / 255.f); }
; __device__ void phase4(const Params& p) {
;     ...
;       if (seg == 0) {
;         #pragma unroll
;         for (int bj = 0; bj < 2; ++bj)
;           #pragma unroll
;           for (int n = 0; n < 2; ++n) {
;             const size_t base = (size_t)EPI_T(bj, n) * D + lanef;
;             const unsigned* pa = reinterpret_cast<const unsigned*>(reinterpret_cast<const unsigned char*>(sga) + base);
;             const unsigned* pb = reinterpret_cast<const unsigned*>(reinterpret_cast<const unsigned char*>(sgb) + base);
;             #pragma unroll
;             for (int ai = 0; ai < 2; ++ai)
;               #pragma unroll
;               for (int m = 0; m < 4; ++m) {
;                 const unsigned ga = pa[(ai * 128 + m * 16) / 4];
;                 const unsigned gb = pb[(ai * 128 + m * 16) / 4];
;                 #pragma unroll
;                 for (int j = 0; j < 4; ++j)
;                   acc[ai][bj][m][n][j] *= u8f(ga, j) * __builtin_amdgcn_rcpf(fmaxf(u8f(gb, j), 1e-30f));
;               }
;             asm volatile("" ::: "memory");
;           }
	v_pk_mul_f32 v[146:147], v[146:147], s[16:17] op_sel_hi:[1,0]
	v_pk_mul_f32 v[140:141], v[140:141], s[16:17] op_sel_hi:[1,0]
	v_pk_mul_f32 v[142:143], v[142:143], s[16:17] op_sel_hi:[1,0]
	v_max_f32_e32 v144, 0xda24260, v144
	v_max_f32_e32 v145, 0xda24260, v145
	v_max_f32_e32 v146, 0xda24260, v146
	v_max_f32_e32 v147, 0xda24260, v147
	v_rcp_f32_e32 v144, v144
	v_rcp_f32_e32 v145, v145
	v_rcp_f32_e32 v146, v146
	v_rcp_f32_e32 v147, v147
	v_pk_mul_f32 v[140:141], v[140:141], v[144:145]
	v_pk_mul_f32 v[142:143], v[142:143], v[146:147]
	v_pk_mul_f32 v[24:25], v[24:25], v[140:141]
	v_pk_mul_f32 v[26:27], v[26:27], v[142:143]
	v_cvt_f32_ubyte0_e32 v144, v202
	v_cvt_f32_ubyte1_e32 v145, v202
	v_cvt_f32_ubyte2_e32 v146, v202
	v_cvt_f32_ubyte3_e32 v147, v202
	v_cvt_f32_ubyte0_e32 v140, v198
	v_cvt_f32_ubyte1_e32 v141, v198
	v_cvt_f32_ubyte2_e32 v142, v198
	v_cvt_f32_ubyte3_e32 v143, v198
	v_pk_mul_f32 v[144:145], v[144:145], s[16:17] op_sel_hi:[1,0]
	v_pk_mul_f32 v[146:147], v[146:147], s[16:17] op_sel_hi:[1,0]
	v_pk_mul_f32 v[140:141], v[140:141], s[16:17] op_sel_hi:[1,0]
	v_pk_mul_f32 v[142:143], v[142:143], s[16:17] op_sel_hi:[1,0]
	v_max_f32_e32 v144, 0xda24260, v144
	v_max_f32_e32 v145, 0xda24260, v145
	v_max_f32_e32 v146, 0xda24260, v146
	v_max_f32_e32 v147, 0xda24260, v147
	v_rcp_f32_e32 v144, v144
	v_rcp_f32_e32 v145, v145
	v_rcp_f32_e32 v146, v146
	v_rcp_f32_e32 v147, v147
	v_pk_mul_f32 v[140:141], v[140:141], v[144:145]
	v_pk_mul_f32 v[142:143], v[142:143], v[146:147]
	v_pk_mul_f32 v[16:17], v[16:17], v[140:141]
	v_pk_mul_f32 v[18:19], v[18:19], v[142:143]
	v_cvt_f32_ubyte0_e32 v144, v203
	v_cvt_f32_ubyte1_e32 v145, v203
	v_cvt_f32_ubyte2_e32 v146, v203
	v_cvt_f32_ubyte3_e32 v147, v203
	v_cvt_f32_ubyte0_e32 v140, v199
	v_cvt_f32_ubyte1_e32 v141, v199
	v_cvt_f32_ubyte2_e32 v142, v199
	v_cvt_f32_ubyte3_e32 v143, v199
	v_pk_mul_f32 v[144:145], v[144:145], s[16:17] op_sel_hi:[1,0]
	v_pk_mul_f32 v[146:147], v[146:147], s[16:17] op_sel_hi:[1,0]
	v_pk_mul_f32 v[140:141], v[140:141], s[16:17] op_sel_hi:[1,0]
	v_pk_mul_f32 v[142:143], v[142:143], s[16:17] op_sel_hi:[1,0]
	v_max_f32_e32 v144, 0xda24260, v144
	v_max_f32_e32 v145, 0xda24260, v145
	v_max_f32_e32 v146, 0xda24260, v146
	v_max_f32_e32 v147, 0xda24260, v147
	v_rcp_f32_e32 v144, v144
	v_rcp_f32_e32 v145, v145
	v_rcp_f32_e32 v146, v146
	v_rcp_f32_e32 v147, v147
	v_pk_mul_f32 v[140:141], v[140:141], v[144:145]
	v_pk_mul_f32 v[142:143], v[142:143], v[146:147]
	v_pk_mul_f32 v[8:9], v[8:9], v[140:141]
	v_pk_mul_f32 v[10:11], v[10:11], v[142:143]
	s_waitcnt vmcnt(2)
	v_permlane16_swap_b32 v204, v205
	v_permlane16_swap_b32 v206, v207
	v_permlane16_swap_b32 v208, v209
	v_permlane16_swap_b32 v210, v211
	v_permlane32_swap_b32 v204, v206
	v_permlane32_swap_b32 v205, v207
	v_permlane32_swap_b32 v208, v210
	v_permlane32_swap_b32 v209, v211
	v_cvt_f32_ubyte0_e32 v144, v208
	v_cvt_f32_ubyte1_e32 v145, v208
	v_cvt_f32_ubyte2_e32 v146, v208
	v_cvt_f32_ubyte3_e32 v147, v208
	v_cvt_f32_ubyte0_e32 v140, v204
	v_cvt_f32_ubyte1_e32 v141, v204
	v_cvt_f32_ubyte2_e32 v142, v204
	v_cvt_f32_ubyte3_e32 v143, v204
	v_pk_mul_f32 v[144:145], v[144:145], s[16:17] op_sel_hi:[1,0]
	v_pk_mul_f32 v[146:147], v[146:147], s[16:17] op_sel_hi:[1,0]
	v_pk_mul_f32 v[140:141], v[140:141], s[16:17] op_sel_hi:[1,0]
	v_pk_mul_f32 v[142:143], v[142:143], s[16:17] op_sel_hi:[1,0]
	v_max_f32_e32 v144, 0xda24260, v144
	v_max_f32_e32 v145, 0xda24260, v145
	v_max_f32_e32 v146, 0xda24260, v146
	v_max_f32_e32 v147, 0xda24260, v147
	v_rcp_f32_e32 v144, v144
	v_rcp_f32_e32 v145, v145
	v_rcp_f32_e32 v146, v146
	v_rcp_f32_e32 v147, v147
	v_pk_mul_f32 v[140:141], v[140:141], v[144:145]
	v_pk_mul_f32 v[142:143], v[142:143], v[146:147]
	v_pk_mul_f32 v[92:93], v[92:93], v[140:141]
	v_pk_mul_f32 v[94:95], v[94:95], v[142:143]
	v_cvt_f32_ubyte0_e32 v144, v209
	v_cvt_f32_ubyte1_e32 v145, v209
	v_cvt_f32_ubyte2_e32 v146, v209
	v_cvt_f32_ubyte3_e32 v147, v209
	v_cvt_f32_ubyte0_e32 v140, v205
	v_cvt_f32_ubyte1_e32 v141, v205
	v_cvt_f32_ubyte2_e32 v142, v205
	v_cvt_f32_ubyte3_e32 v143, v205
	v_pk_mul_f32 v[144:145], v[144:145], s[16:17] op_sel_hi:[1,0]
	v_pk_mul_f32 v[146:147], v[146:147], s[16:17] op_sel_hi:[1,0]
	v_pk_mul_f32 v[140:141], v[140:141], s[16:17] op_sel_hi:[1,0]
	v_pk_mul_f32 v[142:143], v[142:143], s[16:17] op_sel_hi:[1,0]
	v_max_f32_e32 v144, 0xda24260, v144
	v_max_f32_e32 v145, 0xda24260, v145
	v_max_f32_e32 v146, 0xda24260, v146
	v_max_f32_e32 v147, 0xda24260, v147
	v_rcp_f32_e32 v144, v144
	v_rcp_f32_e32 v145, v145
	v_rcp_f32_e32 v146, v146
	v_rcp_f32_e32 v147, v147
	v_pk_mul_f32 v[140:141], v[140:141], v[144:145]
	v_pk_mul_f32 v[142:143], v[142:143], v[146:147]
	v_pk_mul_f32 v[84:85], v[84:85], v[140:141]
	v_pk_mul_f32 v[86:87], v[86:87], v[142:143]
	v_cvt_f32_ubyte0_e32 v144, v210
	v_cvt_f32_ubyte1_e32 v145, v210
	v_cvt_f32_ubyte2_e32 v146, v210
	v_cvt_f32_ubyte3_e32 v147, v210
	v_cvt_f32_ubyte0_e32 v140, v206
	v_cvt_f32_ubyte1_e32 v141, v206
	v_cvt_f32_ubyte2_e32 v142, v206
	v_cvt_f32_ubyte3_e32 v143, v206
	v_pk_mul_f32 v[144:145], v[144:145], s[16:17] op_sel_hi:[1,0]
	v_pk_mul_f32 v[146:147], v[146:147], s[16:17] op_sel_hi:[1,0]
	v_pk_mul_f32 v[140:141], v[140:141], s[16:17] op_sel_hi:[1,0]
	v_pk_mul_f32 v[142:143], v[142:143], s[16:17] op_sel_hi:[1,0]
	v_max_f32_e32 v144, 0xda24260, v144
	v_max_f32_e32 v145, 0xda24260, v145
	v_max_f32_e32 v146, 0xda24260, v146
	v_max_f32_e32 v147, 0xda24260, v147
	v_rcp_f32_e32 v144, v144
	v_rcp_f32_e32 v145, v145
	v_rcp_f32_e32 v146, v146
	v_rcp_f32_e32 v147, v147
	v_pk_mul_f32 v[140:141], v[140:141], v[144:145]
	v_pk_mul_f32 v[142:143], v[142:143], v[146:147]
	v_pk_mul_f32 v[76:77], v[76:77], v[140:141]
	v_pk_mul_f32 v[78:79], v[78:79], v[142:143]
	v_cvt_f32_ubyte0_e32 v144, v211
	v_cvt_f32_ubyte1_e32 v145, v211
	v_cvt_f32_ubyte2_e32 v146, v211
	v_cvt_f32_ubyte3_e32 v147, v211
	v_cvt_f32_ubyte0_e32 v140, v207
	v_cvt_f32_ubyte1_e32 v141, v207
	v_cvt_f32_ubyte2_e32 v142, v207
	v_cvt_f32_ubyte3_e32 v143, v207
	v_pk_mul_f32 v[144:145], v[144:145], s[16:17] op_sel_hi:[1,0]
	v_pk_mul_f32 v[146:147], v[146:147], s[16:17] op_sel_hi:[1,0]
	v_pk_mul_f32 v[140:141], v[140:141], s[16:17] op_sel_hi:[1,0]
	v_pk_mul_f32 v[142:143], v[142:143], s[16:17] op_sel_hi:[1,0]
	v_max_f32_e32 v144, 0xda24260, v144
	v_max_f32_e32 v145, 0xda24260, v145
	v_max_f32_e32 v146, 0xda24260, v146
	v_max_f32_e32 v147, 0xda24260, v147
	v_rcp_f32_e32 v144, v144
	v_rcp_f32_e32 v145, v145
	v_rcp_f32_e32 v146, v146
	v_rcp_f32_e32 v147, v147
	v_pk_mul_f32 v[140:141], v[140:141], v[144:145]
	v_pk_mul_f32 v[142:143], v[142:143], v[146:147]
	v_pk_mul_f32 v[68:69], v[68:69], v[140:141]
	v_pk_mul_f32 v[70:71], v[70:71], v[142:143]
	s_waitcnt vmcnt(0)
; __device__ __forceinline__ float u8f(unsigned w, int i) { return (float)((w >> (8 * i)) & 0xffu) * (1.f / 255.f); }
; __device__ __forceinline__ bool tile_coords(int it, int nM, int nN, int& pm, int& pn) {
;   const int G = gridDim.x, b = blockIdx.x, ntiles = nM * nN;
;   int L;
;   if ((G & 7) == 0 && (it + 1) * G <= ntiles) L = it * G + (b & 7) * (G >> 3) + (b >> 3);
;   else L = it * G + b;
;   if (L >= ntiles) return false;
;   const int nig = 8 * nN, gid = L / nig, fm = gid * 8, gsz = min(nM - fm, 8);
;   pm = fm + (L % nig) % gsz;
;   pn = (L % nig) / gsz;
;   return true;
; __device__ void phase4(const Params& p) {
;     ...
;       if (seg == 0) {
;         #pragma unroll
;         for (int bj = 0; bj < 2; ++bj)
;           #pragma unroll
;           for (int n = 0; n < 2; ++n) {
;             const size_t base = (size_t)EPI_T(bj, n) * D + lanef;
;             const unsigned* pa = reinterpret_cast<const unsigned*>(reinterpret_cast<const unsigned char*>(sga) + base);
;             const unsigned* pb = reinterpret_cast<const unsigned*>(reinterpret_cast<const unsigned char*>(sgb) + base);
;             #pragma unroll
;             for (int ai = 0; ai < 2; ++ai)
;               #pragma unroll
;               for (int m = 0; m < 4; ++m) {
;                 const unsigned ga = pa[(ai * 128 + m * 16) / 4];
;                 const unsigned gb = pb[(ai * 128 + m * 16) / 4];
;                 #pragma unroll
;                 for (int j = 0; j < 4; ++j)
;                   acc[ai][bj][m][n][j] *= u8f(ga, j) * __builtin_amdgcn_rcpf(fmaxf(u8f(gb, j), 1e-30f));
;               }
;             asm volatile("" ::: "memory");
;           }
	v_permlane16_swap_b32 v212, v213
	v_permlane16_swap_b32 v214, v215
	v_permlane16_swap_b32 v216, v217
	v_permlane16_swap_b32 v218, v219
	v_permlane32_swap_b32 v212, v214
	v_permlane32_swap_b32 v213, v215
	v_permlane32_swap_b32 v216, v218
	v_permlane32_swap_b32 v217, v219
	v_cvt_f32_ubyte0_e32 v144, v216
	v_cvt_f32_ubyte1_e32 v145, v216
	v_cvt_f32_ubyte2_e32 v146, v216
	v_cvt_f32_ubyte3_e32 v147, v216
	v_cvt_f32_ubyte0_e32 v140, v212
	v_cvt_f32_ubyte1_e32 v141, v212
	v_cvt_f32_ubyte2_e32 v142, v212
	v_cvt_f32_ubyte3_e32 v143, v212
	v_pk_mul_f32 v[144:145], v[144:145], s[16:17] op_sel_hi:[1,0]
	v_pk_mul_f32 v[146:147], v[146:147], s[16:17] op_sel_hi:[1,0]
	v_pk_mul_f32 v[140:141], v[140:141], s[16:17] op_sel_hi:[1,0]
	v_pk_mul_f32 v[142:143], v[142:143], s[16:17] op_sel_hi:[1,0]
	v_max_f32_e32 v144, 0xda24260, v144
	v_max_f32_e32 v145, 0xda24260, v145
	v_max_f32_e32 v146, 0xda24260, v146
	v_max_f32_e32 v147, 0xda24260, v147
	v_rcp_f32_e32 v144, v144
	v_rcp_f32_e32 v145, v145
	v_rcp_f32_e32 v146, v146
	v_rcp_f32_e32 v147, v147
	v_pk_mul_f32 v[140:141], v[140:141], v[144:145]
	v_pk_mul_f32 v[142:143], v[142:143], v[146:147]
	v_pk_mul_f32 v[28:29], v[28:29], v[140:141]
	v_pk_mul_f32 v[30:31], v[30:31], v[142:143]
	v_cvt_f32_ubyte0_e32 v144, v217
	v_cvt_f32_ubyte1_e32 v145, v217
	v_cvt_f32_ubyte2_e32 v146, v217
	v_cvt_f32_ubyte3_e32 v147, v217
	v_cvt_f32_ubyte0_e32 v140, v213
	v_cvt_f32_ubyte1_e32 v141, v213
	v_cvt_f32_ubyte2_e32 v142, v213
	v_cvt_f32_ubyte3_e32 v143, v213
	v_pk_mul_f32 v[144:145], v[144:145], s[16:17] op_sel_hi:[1,0]
	v_pk_mul_f32 v[146:147], v[146:147], s[16:17] op_sel_hi:[1,0]
	v_pk_mul_f32 v[140:141], v[140:141], s[16:17] op_sel_hi:[1,0]
	v_pk_mul_f32 v[142:143], v[142:143], s[16:17] op_sel_hi:[1,0]
	v_max_f32_e32 v144, 0xda24260, v144
	v_max_f32_e32 v145, 0xda24260, v145
	v_max_f32_e32 v146, 0xda24260, v146
	v_max_f32_e32 v147, 0xda24260, v147
	v_rcp_f32_e32 v144, v144
	v_rcp_f32_e32 v145, v145
	v_rcp_f32_e32 v146, v146
	v_rcp_f32_e32 v147, v147
	v_pk_mul_f32 v[140:141], v[140:141], v[144:145]
	v_pk_mul_f32 v[142:143], v[142:143], v[146:147]
	v_pk_mul_f32 v[20:21], v[20:21], v[140:141]
	v_pk_mul_f32 v[22:23], v[22:23], v[142:143]
	v_cvt_f32_ubyte0_e32 v144, v218
	v_cvt_f32_ubyte1_e32 v145, v218
	v_cvt_f32_ubyte2_e32 v146, v218
	v_cvt_f32_ubyte3_e32 v147, v218
	v_cvt_f32_ubyte0_e32 v140, v214
	v_cvt_f32_ubyte1_e32 v141, v214
	v_cvt_f32_ubyte2_e32 v142, v214
	v_cvt_f32_ubyte3_e32 v143, v214
	v_pk_mul_f32 v[144:145], v[144:145], s[16:17] op_sel_hi:[1,0]
	v_pk_mul_f32 v[146:147], v[146:147], s[16:17] op_sel_hi:[1,0]
	v_pk_mul_f32 v[140:141], v[140:141], s[16:17] op_sel_hi:[1,0]
	v_pk_mul_f32 v[142:143], v[142:143], s[16:17] op_sel_hi:[1,0]
	v_max_f32_e32 v144, 0xda24260, v144
	v_max_f32_e32 v145, 0xda24260, v145
	v_max_f32_e32 v146, 0xda24260, v146
	v_max_f32_e32 v147, 0xda24260, v147
	v_rcp_f32_e32 v144, v144
	v_rcp_f32_e32 v145, v145
	v_rcp_f32_e32 v146, v146
	v_rcp_f32_e32 v147, v147
	v_pk_mul_f32 v[140:141], v[140:141], v[144:145]
	v_pk_mul_f32 v[142:143], v[142:143], v[146:147]
	v_pk_mul_f32 v[12:13], v[12:13], v[140:141]
	v_pk_mul_f32 v[14:15], v[14:15], v[142:143]
	v_cvt_f32_ubyte0_e32 v144, v219
	v_cvt_f32_ubyte1_e32 v145, v219
	v_cvt_f32_ubyte2_e32 v146, v219
	v_cvt_f32_ubyte3_e32 v147, v219
	v_cvt_f32_ubyte0_e32 v140, v215
	v_cvt_f32_ubyte1_e32 v141, v215
	v_cvt_f32_ubyte2_e32 v142, v215
	v_cvt_f32_ubyte3_e32 v143, v215
	v_pk_mul_f32 v[144:145], v[144:145], s[16:17] op_sel_hi:[1,0]
	v_pk_mul_f32 v[146:147], v[146:147], s[16:17] op_sel_hi:[1,0]
	v_pk_mul_f32 v[140:141], v[140:141], s[16:17] op_sel_hi:[1,0]
	v_pk_mul_f32 v[142:143], v[142:143], s[16:17] op_sel_hi:[1,0]
	v_max_f32_e32 v144, 0xda24260, v144
	v_max_f32_e32 v145, 0xda24260, v145
	v_max_f32_e32 v146, 0xda24260, v146
	v_max_f32_e32 v147, 0xda24260, v147
	v_rcp_f32_e32 v144, v144
	v_rcp_f32_e32 v145, v145
	v_rcp_f32_e32 v146, v146
	v_rcp_f32_e32 v147, v147
	v_pk_mul_f32 v[140:141], v[140:141], v[144:145]
	v_pk_mul_f32 v[142:143], v[142:143], v[146:147]
	v_pk_mul_f32 v[4:5], v[4:5], v[140:141]
	v_pk_mul_f32 v[6:7], v[6:7], v[142:143]
	s_branch .LBB0_599
.Lp4e_seg1:
	s_add_i32 s92, s77, 1
	s_mul_i32 s93, s92, s33
	s_add_i32 s96, s93, s33
	s_mov_b32 s97, s2
	s_and_b32 s98, s33, 7
	s_cmp_lg_u32 s98, 0
	s_cbranch_scc1 .Lp4n_base
	s_cmpk_gt_i32 s96, 0x500
	s_cbranch_scc1 .Lp4n_base
	s_mov_b32 s97, s35
.Lp4n_base:
	s_add_i32 s92, s97, s93
	s_cmpk_gt_i32 s92, 0x4ff
	s_cbranch_scc1 .Lp4n_done
	s_lshr_b32 s93, s92, 6
	s_and_b32 s96, s92, 7
	s_lshl_b32 s93, s93, 3
	s_add_i32 s93, s93, s96
	s_lshl_b32 s93, s93, 8
	s_bfe_u32 s96, s92, 0x30003
	s_lshl_b32 s96, s96, 8
	v_and_b32_e32 v242, 0xff, v194
	v_lshrrev_b32_e32 v243, 8, v194
	v_lshlrev_b32_e32 v243, 7, v243
	v_add_u32_e32 v244, s96, v242
	v_lshl_add_u32 v244, v244, 12, v243
	v_add_u32_e32 v244, 0x2900000, v244
	global_load_dword v246, v244, s[30:31]
	v_add_u32_e32 v245, s93, v242
	v_lshl_add_u32 v245, v245, 12, v243
	global_load_dword v247, v245, s[28:29]
